# PGATE/EpiRes/CIN GEMM instances: both per-tile accumulator clears removed, first K-loop iteration peeled with C=0
# speedup vs baseline: 1.0079x; 1.0079x over previous
; #define PG8_STAGE(bufoff, gbase, voff) do { _Pragma("unroll") for (int _i = 0; _i < 2; ++_i) \
;         __builtin_amdgcn_global_load_lds((const unsigned*)((const char*)(gbase) + (voff)[_i]), (LAS unsigned*)(lds + (bufoff) + ldsw + _i * 8192), 16, 0, 0); } while (0)
; #define PG8_LDA(dst, b, h) do { _Pragma("unroll") for (int m = 0; m < 4; ++m) _Pragma("unroll") for (int k = 0; k < 2; ++k) dst[m][k] = *(const LAS bf16x8*)(lds + PG8_SA(b, h) + aoff + m * 2048 + k * 1024); } while (0)
; #define PG8_LDB(dst, b, h) do { _Pragma("unroll") for (int n = 0; n < 2; ++n) _Pragma("unroll") for (int k = 0; k < 2; ++k) dst[n][k] = *(const LAS bf16x8*)(lds + PG8_SB(b, h) + boff + n * 2048 + k * 1024); } while (0)
; #define PG8_MMA(ai, bj, At, Bt) do { __builtin_amdgcn_s_setprio(1); _Pragma("unroll") for (int k = 0; k < 2; ++k) _Pragma("unroll") for (int m = 0; m < 4; ++m) _Pragma("unroll") for (int n = 0; n < 2; ++n) \
;         acc[ai][bj][m][n] = __builtin_amdgcn_mfma_f32_16x16x32_bf16(Bt[n][k], At[m][k], acc[ai][bj][m][n], 0, 0, 0); __builtin_amdgcn_s_setprio(0); } while (0)
; template <class Epi, bool ALIGN_EPI>
; __device__ __forceinline__ void gemm_phase(LAS unsigned char* lds, const Gemm g, const StaticOrder& S, const Epi& E, const int tid) {
;     ...
;         const bool has_next = S.next(ui + 1, nxt);
;         const char* nA = has_next ? (const char*)g.A + (size_t)nxt.pm * tA + (size_t)nxt.pn * g.apn * 2 : cA; const char* nB = has_next ? (const char*)g.Bt + (size_t)nxt.pn * tB : cB;
;         for (int t = 0; t < nt; t += 2) {
;             const bool last = (t == nt - 2);
;             const char* a1 = cA + (size_t)(t + 1) * kstep;
;             const char* a2 = last ? nA : cA + (size_t)(t + 2) * kstep; const char* b2 = last ? nB : cB + (size_t)(t + 2) * kstep;
;             const char* a3 = a2 + kstep; const char* b3 = b2 + kstep;
;             PG8_LDB(B0, 0, 0); PG8_LDB(B1, 0, 1); PG8_SCHED; PG8_LDA(At, 0, 0); PG8_STAGE(PG8_SA(1, 1), a1 + hA, voffA);
;             PG8_WAIT_V(8); PG8_WAIT_L(0); PG8_BAR; PG8_MMA(0, 0, At, B0); PG8_MMA(0, 1, At, B1); PG8_BAR; PG8_SCHED;
;             PG8_LDA(At, 0, 1); PG8_STAGE(PG8_SB(0, 0), b2, voffB); PG8_STAGE(PG8_SB(0, 1), b2 + hB, voffB); PG8_STAGE(PG8_SA(0, 0), a2, voffA);
;             PG8_WAIT_V(8); PG8_WAIT_L(0); PG8_BAR; PG8_MMA(1, 0, At, B0); PG8_MMA(1, 1, At, B1); PG8_BAR; PG8_SCHED;
.LBB0_234:
	s_andn2_b64 vcc, exec, s[36:37]
	s_waitcnt lgkmcnt(0)
	s_cbranch_vccnz .LBB0_238
	s_add_u32 s12, s46, 0x100
	v_lshl_add_u64 v[128:129], v[128:129], 0, s[92:93]
	s_addc_u32 s13, s47, 0
	s_mov_b32 s46, 0
	s_add_i32 s47, s46, 2
	s_cmp_eq_u32 s60, s46
	s_cselect_b64 vcc, -1, 0
	s_cselect_b32 s71, s15, s13
	s_cselect_b32 s70, s14, s12
	s_add_i32 s46, 0, 0x14000
	v_lshl_add_u64 v[130:131], v[128:129], 0, s[92:93]
	v_add_u32_e32 v142, s33, v218
	v_add_u32_e32 v166, s46, v218
	v_cndmask_b32_e32 v159, v131, v165, vcc
	v_cndmask_b32_e32 v158, v130, v164, vcc
	ds_read_b128 v[130:133], v142
	ds_read_b128 v[134:137], v142 offset:1024
	ds_read_b128 v[138:141], v142 offset:2048
	ds_read_b128 v[142:145], v142 offset:3072
	ds_read_b128 v[146:149], v166
	ds_read_b128 v[150:153], v166 offset:1024
	ds_read_b128 v[154:157], v166 offset:2048
	ds_read_b128 v[186:189], v166 offset:3072
	v_lshl_add_u64 v[166:167], v[128:129], 0, v[160:161]
	s_add_i32 m0, s53, 0xc000
	ds_read_b128 v[190:193], v219
	ds_read_b128 v[194:197], v219 offset:1024
	ds_read_b128 v[198:201], v219 offset:2048
	ds_read_b128 v[202:205], v219 offset:3072
	ds_read_b128 v[206:209], v219 offset:4096
	ds_read_b128 v[210:213], v219 offset:5120
	ds_read_b128 v[240:243], v219 offset:6144
	ds_read_b128 v[244:247], v219 offset:7168
	global_load_lds_dwordx4 v[166:167], off
	v_lshl_add_u64 v[166:167], v[128:129], 0, v[162:163]
	s_add_i32 m0, s53, 0xe000
	s_nop 0
	global_load_lds_dwordx4 v[166:167], off
	s_waitcnt vmcnt(8)
	s_waitcnt lgkmcnt(0)
	s_barrier
	s_setprio 1
	s_waitcnt lgkmcnt(0)
	v_mfma_f32_16x16x32_bf16 v[120:123], v[130:133], v[190:193], 0
	v_mfma_f32_16x16x32_bf16 v[124:127], v[138:141], v[190:193], 0
	v_mfma_f32_16x16x32_bf16 v[108:111], v[130:133], v[198:201], 0
	v_mfma_f32_16x16x32_bf16 v[104:107], v[138:141], v[198:201], 0
	v_mfma_f32_16x16x32_bf16 v[92:95], v[130:133], v[206:209], 0
	v_mfma_f32_16x16x32_bf16 v[88:91], v[138:141], v[206:209], 0
	v_mfma_f32_16x16x32_bf16 v[76:79], v[130:133], v[240:243], 0
	v_mfma_f32_16x16x32_bf16 v[72:75], v[138:141], v[240:243], 0
	v_mfma_f32_16x16x32_bf16 v[120:123], v[134:137], v[194:197], v[120:123]
	v_mfma_f32_16x16x32_bf16 v[124:127], v[142:145], v[194:197], v[124:127]
	v_mfma_f32_16x16x32_bf16 v[108:111], v[134:137], v[202:205], v[108:111]
	v_mfma_f32_16x16x32_bf16 v[104:107], v[142:145], v[202:205], v[104:107]
	v_mfma_f32_16x16x32_bf16 v[92:95], v[134:137], v[210:213], v[92:95]
	v_mfma_f32_16x16x32_bf16 v[88:91], v[142:145], v[210:213], v[88:91]
	v_mfma_f32_16x16x32_bf16 v[76:79], v[134:137], v[244:247], v[76:79]
	v_mfma_f32_16x16x32_bf16 v[72:75], v[142:145], v[244:247], v[72:75]
	s_setprio 0
	s_setprio 1
	v_mfma_f32_16x16x32_bf16 v[116:119], v[146:149], v[190:193], 0
	v_mfma_f32_16x16x32_bf16 v[112:115], v[154:157], v[190:193], 0
	v_mfma_f32_16x16x32_bf16 v[100:103], v[146:149], v[198:201], 0
	v_mfma_f32_16x16x32_bf16 v[96:99], v[154:157], v[198:201], 0
	v_mfma_f32_16x16x32_bf16 v[84:87], v[146:149], v[206:209], 0
	v_mfma_f32_16x16x32_bf16 v[80:83], v[154:157], v[206:209], 0
	v_mfma_f32_16x16x32_bf16 v[68:71], v[146:149], v[240:243], 0
	v_mfma_f32_16x16x32_bf16 v[64:67], v[154:157], v[240:243], 0
	v_mfma_f32_16x16x32_bf16 v[116:119], v[150:153], v[194:197], v[116:119]
	v_mfma_f32_16x16x32_bf16 v[112:115], v[186:189], v[194:197], v[112:115]
	v_mfma_f32_16x16x32_bf16 v[100:103], v[150:153], v[202:205], v[100:103]
	v_mfma_f32_16x16x32_bf16 v[96:99], v[186:189], v[202:205], v[96:99]
	v_mfma_f32_16x16x32_bf16 v[84:87], v[150:153], v[210:213], v[84:87]
	v_mfma_f32_16x16x32_bf16 v[80:83], v[186:189], v[210:213], v[80:83]
	v_mfma_f32_16x16x32_bf16 v[68:71], v[150:153], v[244:247], v[68:71]
	v_mfma_f32_16x16x32_bf16 v[64:67], v[186:189], v[244:247], v[64:67]
	s_setprio 0
	s_barrier
	s_add_i32 s72, s33, s52
	v_lshl_add_u64 v[166:167], s[70:71], 0, v[180:181]
	s_mov_b32 m0, s72
	ds_read_b128 v[190:193], v219 offset:16384
	ds_read_b128 v[194:197], v219 offset:17408
	ds_read_b128 v[198:201], v219 offset:18432
	ds_read_b128 v[202:205], v219 offset:19456
	ds_read_b128 v[206:209], v219 offset:20480
	ds_read_b128 v[210:213], v219 offset:21504
	ds_read_b128 v[240:243], v219 offset:22528
	ds_read_b128 v[244:247], v219 offset:23552
	global_load_lds_dwordx4 v[166:167], off
	s_add_i32 m0, s72, 0x2000
	v_lshl_add_u64 v[214:215], s[70:71], 0, v[184:185]
	s_add_u32 s70, s70, s49
	s_addc_u32 s71, s71, 0
	s_add_i32 s46, s46, s52
	global_load_lds_dwordx4 v[214:215], off
	v_lshl_add_u64 v[220:221], s[70:71], 0, v[180:181]
	s_mov_b32 m0, s46
	v_lshl_add_u64 v[226:227], s[70:71], 0, v[184:185]
	global_load_lds_dwordx4 v[220:221], off
	s_add_i32 m0, s46, 0x2000
	v_lshl_add_u64 v[248:249], v[158:159], 0, v[178:179]
	global_load_lds_dwordx4 v[226:227], off
	s_mov_b32 m0, s53
	v_lshl_add_u64 v[250:251], v[158:159], 0, v[182:183]
	global_load_lds_dwordx4 v[248:249], off
	s_mov_b32 m0, s54
	s_nop 0
	global_load_lds_dwordx4 v[250:251], off
	s_waitcnt vmcnt(8)
	s_waitcnt lgkmcnt(0)
	s_barrier
; #define PG8_STAGE(bufoff, gbase, voff) do { _Pragma("unroll") for (int _i = 0; _i < 2; ++_i) \
;         __builtin_amdgcn_global_load_lds((const unsigned*)((const char*)(gbase) + (voff)[_i]), (LAS unsigned*)(lds + (bufoff) + ldsw + _i * 8192), 16, 0, 0); } while (0)
; #define PG8_LDA(dst, b, h) do { _Pragma("unroll") for (int m = 0; m < 4; ++m) _Pragma("unroll") for (int k = 0; k < 2; ++k) dst[m][k] = *(const LAS bf16x8*)(lds + PG8_SA(b, h) + aoff + m * 2048 + k * 1024); } while (0)
; #define PG8_LDB(dst, b, h) do { _Pragma("unroll") for (int n = 0; n < 2; ++n) _Pragma("unroll") for (int k = 0; k < 2; ++k) dst[n][k] = *(const LAS bf16x8*)(lds + PG8_SB(b, h) + boff + n * 2048 + k * 1024); } while (0)
; #define PG8_MMA(ai, bj, At, Bt) do { __builtin_amdgcn_s_setprio(1); _Pragma("unroll") for (int k = 0; k < 2; ++k) _Pragma("unroll") for (int m = 0; m < 4; ++m) _Pragma("unroll") for (int n = 0; n < 2; ++n) \
;         acc[ai][bj][m][n] = __builtin_amdgcn_mfma_f32_16x16x32_bf16(Bt[n][k], At[m][k], acc[ai][bj][m][n], 0, 0, 0); __builtin_amdgcn_s_setprio(0); } while (0)
; #define PG8_WAIT_V(n) asm volatile("s_waitcnt vmcnt(" #n ")" ::: "memory")
; #define PG8_WAIT_L(n) asm volatile("s_waitcnt lgkmcnt(" #n ")" ::: "memory")
; #define PG8_BAR __builtin_amdgcn_s_barrier()
; #define PG8_SCHED __builtin_amdgcn_sched_barrier(0)
; template <class Epi, bool ALIGN_EPI>
; __device__ __forceinline__ void gemm_phase(LAS unsigned char* lds, const Gemm g, const StaticOrder& S, const Epi& E, const int tid) {
;     ...
;             PG8_WAIT_V(8); PG8_WAIT_L(0); PG8_BAR; PG8_MMA(1, 0, At, B0); PG8_MMA(1, 1, At, B1); PG8_BAR; PG8_SCHED;
;             PG8_LDB(B0, 1, 0); PG8_LDB(B1, 1, 1); PG8_SCHED; PG8_LDA(At, 1, 0); PG8_STAGE(PG8_SA(0, 1), a2 + hA, voffA);
;             PG8_WAIT_V(8); PG8_WAIT_L(0); PG8_BAR; PG8_MMA(0, 0, At, B0); PG8_MMA(0, 1, At, B1); PG8_BAR; PG8_SCHED;
;             PG8_LDA(At, 1, 1); PG8_STAGE(PG8_SB(1, 0), b3, voffB); PG8_STAGE(PG8_SB(1, 1), b3 + hB, voffB); PG8_STAGE(PG8_SA(1, 0), a3, voffA);
	s_setprio 1
	s_waitcnt lgkmcnt(0)
	v_mfma_f32_16x16x32_bf16 v[60:63], v[130:133], v[190:193], 0
	v_mfma_f32_16x16x32_bf16 v[56:59], v[138:141], v[190:193], 0
	v_mfma_f32_16x16x32_bf16 v[44:47], v[130:133], v[198:201], 0
	v_mfma_f32_16x16x32_bf16 v[40:43], v[138:141], v[198:201], 0
	v_mfma_f32_16x16x32_bf16 v[28:31], v[130:133], v[206:209], 0
	v_mfma_f32_16x16x32_bf16 v[24:27], v[138:141], v[206:209], 0
	v_mfma_f32_16x16x32_bf16 v[12:15], v[130:133], v[240:243], 0
	v_mfma_f32_16x16x32_bf16 v[8:11], v[138:141], v[240:243], 0
	v_mfma_f32_16x16x32_bf16 v[60:63], v[134:137], v[194:197], v[60:63]
	v_mfma_f32_16x16x32_bf16 v[56:59], v[142:145], v[194:197], v[56:59]
	v_mfma_f32_16x16x32_bf16 v[44:47], v[134:137], v[202:205], v[44:47]
	v_mfma_f32_16x16x32_bf16 v[40:43], v[142:145], v[202:205], v[40:43]
	v_mfma_f32_16x16x32_bf16 v[28:31], v[134:137], v[210:213], v[28:31]
	v_mfma_f32_16x16x32_bf16 v[24:27], v[142:145], v[210:213], v[24:27]
	v_mfma_f32_16x16x32_bf16 v[12:15], v[134:137], v[244:247], v[12:15]
	v_mfma_f32_16x16x32_bf16 v[8:11], v[142:145], v[244:247], v[8:11]
	s_setprio 0
	s_setprio 1
	v_mfma_f32_16x16x32_bf16 v[52:55], v[146:149], v[190:193], 0
	v_mfma_f32_16x16x32_bf16 v[48:51], v[154:157], v[190:193], 0
	v_mfma_f32_16x16x32_bf16 v[36:39], v[146:149], v[198:201], 0
	v_mfma_f32_16x16x32_bf16 v[32:35], v[154:157], v[198:201], 0
	v_mfma_f32_16x16x32_bf16 v[20:23], v[146:149], v[206:209], 0
	v_mfma_f32_16x16x32_bf16 v[16:19], v[154:157], v[206:209], 0
	v_mfma_f32_16x16x32_bf16 v[4:7], v[146:149], v[240:243], 0
	v_mfma_f32_16x16x32_bf16 v[0:3], v[154:157], v[240:243], 0
	v_mfma_f32_16x16x32_bf16 v[52:55], v[150:153], v[194:197], v[52:55]
	v_mfma_f32_16x16x32_bf16 v[48:51], v[186:189], v[194:197], v[48:51]
	v_mfma_f32_16x16x32_bf16 v[36:39], v[150:153], v[202:205], v[36:39]
	v_mfma_f32_16x16x32_bf16 v[32:35], v[186:189], v[202:205], v[32:35]
	v_mfma_f32_16x16x32_bf16 v[20:23], v[150:153], v[210:213], v[20:23]
	v_mfma_f32_16x16x32_bf16 v[16:19], v[186:189], v[210:213], v[16:19]
	v_mfma_f32_16x16x32_bf16 v[4:7], v[150:153], v[244:247], v[4:7]
	v_mfma_f32_16x16x32_bf16 v[0:3], v[186:189], v[244:247], v[0:3]
	s_setprio 0
	s_barrier
	s_add_i32 s46, 0, 0x18000
	s_add_i32 s70, 0, 0x1c000
	v_add_u32_e32 v142, s46, v218
	v_add_u32_e32 v168, s70, v218
	ds_read_b128 v[130:133], v142
	ds_read_b128 v[134:137], v142 offset:1024
	ds_read_b128 v[138:141], v142 offset:2048
	ds_read_b128 v[142:145], v142 offset:3072
	ds_read_b128 v[146:149], v168
	ds_read_b128 v[150:153], v168 offset:1024
	ds_read_b128 v[154:157], v168 offset:2048
	ds_read_b128 v[186:189], v168 offset:3072
	v_lshl_add_u64 v[158:159], v[158:159], 0, s[94:95]
	s_mov_b32 m0, s55
	v_lshl_add_u64 v[252:253], v[158:159], 0, v[178:179]
	ds_read_b128 v[190:193], v219 offset:32768
	ds_read_b128 v[194:197], v219 offset:33792
	ds_read_b128 v[198:201], v219 offset:34816
	ds_read_b128 v[202:205], v219 offset:35840
	ds_read_b128 v[206:209], v219 offset:36864
	ds_read_b128 v[210:213], v219 offset:37888
	ds_read_b128 v[240:243], v219 offset:38912
	ds_read_b128 v[244:247], v219 offset:39936
	global_load_lds_dwordx4 v[252:253], off
	v_lshl_add_u64 v[158:159], v[158:159], 0, v[182:183]
	s_mov_b32 m0, s56
	s_nop 0
	global_load_lds_dwordx4 v[158:159], off
	s_waitcnt vmcnt(8)
	s_waitcnt lgkmcnt(0)
	s_barrier
	s_setprio 1
	s_waitcnt lgkmcnt(0)
	v_mfma_f32_16x16x32_bf16 v[120:123], v[130:133], v[190:193], v[120:123]
	v_mfma_f32_16x16x32_bf16 v[124:127], v[138:141], v[190:193], v[124:127]
	v_mfma_f32_16x16x32_bf16 v[108:111], v[130:133], v[198:201], v[108:111]
	v_mfma_f32_16x16x32_bf16 v[104:107], v[138:141], v[198:201], v[104:107]
	v_mfma_f32_16x16x32_bf16 v[92:95], v[130:133], v[206:209], v[92:95]
	v_mfma_f32_16x16x32_bf16 v[88:91], v[138:141], v[206:209], v[88:91]
	v_mfma_f32_16x16x32_bf16 v[76:79], v[130:133], v[240:243], v[76:79]
	v_mfma_f32_16x16x32_bf16 v[72:75], v[138:141], v[240:243], v[72:75]
	v_mfma_f32_16x16x32_bf16 v[120:123], v[134:137], v[194:197], v[120:123]
	v_mfma_f32_16x16x32_bf16 v[124:127], v[142:145], v[194:197], v[124:127]
	v_mfma_f32_16x16x32_bf16 v[108:111], v[134:137], v[202:205], v[108:111]
	v_mfma_f32_16x16x32_bf16 v[104:107], v[142:145], v[202:205], v[104:107]
	v_mfma_f32_16x16x32_bf16 v[92:95], v[134:137], v[210:213], v[92:95]
	v_mfma_f32_16x16x32_bf16 v[88:91], v[142:145], v[210:213], v[88:91]
	v_mfma_f32_16x16x32_bf16 v[76:79], v[134:137], v[244:247], v[76:79]
	v_mfma_f32_16x16x32_bf16 v[72:75], v[142:145], v[244:247], v[72:75]
	s_setprio 0
	s_setprio 1
	v_mfma_f32_16x16x32_bf16 v[116:119], v[146:149], v[190:193], v[116:119]
	v_mfma_f32_16x16x32_bf16 v[112:115], v[154:157], v[190:193], v[112:115]
	v_mfma_f32_16x16x32_bf16 v[100:103], v[146:149], v[198:201], v[100:103]
	v_mfma_f32_16x16x32_bf16 v[96:99], v[154:157], v[198:201], v[96:99]
	v_mfma_f32_16x16x32_bf16 v[84:87], v[146:149], v[206:209], v[84:87]
	v_mfma_f32_16x16x32_bf16 v[80:83], v[154:157], v[206:209], v[80:83]
	v_mfma_f32_16x16x32_bf16 v[68:71], v[146:149], v[240:243], v[68:71]
	v_mfma_f32_16x16x32_bf16 v[64:67], v[154:157], v[240:243], v[64:67]
	v_mfma_f32_16x16x32_bf16 v[116:119], v[150:153], v[194:197], v[116:119]
	v_mfma_f32_16x16x32_bf16 v[112:115], v[186:189], v[194:197], v[112:115]
	v_mfma_f32_16x16x32_bf16 v[100:103], v[150:153], v[202:205], v[100:103]
	v_mfma_f32_16x16x32_bf16 v[96:99], v[186:189], v[202:205], v[96:99]
	v_mfma_f32_16x16x32_bf16 v[84:87], v[150:153], v[210:213], v[84:87]
	v_mfma_f32_16x16x32_bf16 v[80:83], v[186:189], v[210:213], v[80:83]
	v_mfma_f32_16x16x32_bf16 v[68:71], v[150:153], v[244:247], v[68:71]
	v_mfma_f32_16x16x32_bf16 v[64:67], v[186:189], v[244:247], v[64:67]
	s_setprio 0
	s_barrier
; #define PG8_STAGE(bufoff, gbase, voff) do { _Pragma("unroll") for (int _i = 0; _i < 2; ++_i) \
;         __builtin_amdgcn_global_load_lds((const unsigned*)((const char*)(gbase) + (voff)[_i]), (LAS unsigned*)(lds + (bufoff) + ldsw + _i * 8192), 16, 0, 0); } while (0)
; #define PG8_LDA(dst, b, h) do { _Pragma("unroll") for (int m = 0; m < 4; ++m) _Pragma("unroll") for (int k = 0; k < 2; ++k) dst[m][k] = *(const LAS bf16x8*)(lds + PG8_SA(b, h) + aoff + m * 2048 + k * 1024); } while (0)
; #define PG8_MMA(ai, bj, At, Bt) do { __builtin_amdgcn_s_setprio(1); _Pragma("unroll") for (int k = 0; k < 2; ++k) _Pragma("unroll") for (int m = 0; m < 4; ++m) _Pragma("unroll") for (int n = 0; n < 2; ++n) \
;         acc[ai][bj][m][n] = __builtin_amdgcn_mfma_f32_16x16x32_bf16(Bt[n][k], At[m][k], acc[ai][bj][m][n], 0, 0, 0); __builtin_amdgcn_s_setprio(0); } while (0)
; #define PG8_WAIT_V(n) asm volatile("s_waitcnt vmcnt(" #n ")" ::: "memory")
; #define PG8_WAIT_L(n) asm volatile("s_waitcnt lgkmcnt(" #n ")" ::: "memory")
; #define PG8_BAR __builtin_amdgcn_s_barrier()
; #define PG8_SCHED __builtin_amdgcn_sched_barrier(0)
; template <class Epi, bool ALIGN_EPI>
; __device__ __forceinline__ void gemm_phase(LAS unsigned char* lds, const Gemm g, const StaticOrder& S, const Epi& E, const int tid) {
;     ...
;             PG8_LDA(At, 1, 1); PG8_STAGE(PG8_SB(1, 0), b3, voffB); PG8_STAGE(PG8_SB(1, 1), b3 + hB, voffB); PG8_STAGE(PG8_SA(1, 0), a3, voffA);
;             PG8_WAIT_V(8); PG8_WAIT_L(0); PG8_BAR; PG8_MMA(1, 0, At, B0); PG8_MMA(1, 1, At, B1); PG8_BAR; PG8_SCHED;
;         }
	s_add_i32 s46, s46, s52
	v_lshl_add_u64 v[158:159], v[166:167], 0, s[92:93]
	s_mov_b32 m0, s46
	ds_read_b128 v[190:193], v219 offset:49152
	ds_read_b128 v[194:197], v219 offset:50176
	ds_read_b128 v[198:201], v219 offset:51200
	ds_read_b128 v[202:205], v219 offset:52224
	ds_read_b128 v[206:209], v219 offset:53248
	ds_read_b128 v[210:213], v219 offset:54272
	ds_read_b128 v[240:243], v219 offset:55296
	ds_read_b128 v[244:247], v219 offset:56320
	global_load_lds_dwordx4 v[158:159], off
	v_lshl_add_u64 v[158:159], v[214:215], 0, s[92:93]
	s_add_i32 m0, s46, 0x2000
	s_add_i32 s46, s70, s52
	global_load_lds_dwordx4 v[158:159], off
	v_lshl_add_u64 v[158:159], v[220:221], 0, s[92:93]
	s_mov_b32 m0, s46
	s_nop 0
	global_load_lds_dwordx4 v[158:159], off
	v_lshl_add_u64 v[158:159], v[226:227], 0, s[92:93]
	s_add_i32 m0, s46, 0x2000
	s_nop 0
	global_load_lds_dwordx4 v[158:159], off
	v_lshl_add_u64 v[158:159], v[248:249], 0, s[92:93]
	s_mov_b32 m0, s57
	s_nop 0
	global_load_lds_dwordx4 v[158:159], off
	v_lshl_add_u64 v[158:159], v[250:251], 0, s[92:93]
	s_mov_b32 m0, s58
	s_nop 0
	global_load_lds_dwordx4 v[158:159], off
	s_waitcnt vmcnt(8)
	s_waitcnt lgkmcnt(0)
	s_barrier
	s_setprio 1
	s_waitcnt lgkmcnt(0)
	v_mfma_f32_16x16x32_bf16 v[60:63], v[130:133], v[190:193], v[60:63]
	v_mfma_f32_16x16x32_bf16 v[56:59], v[138:141], v[190:193], v[56:59]
	v_mfma_f32_16x16x32_bf16 v[44:47], v[130:133], v[198:201], v[44:47]
	v_mfma_f32_16x16x32_bf16 v[40:43], v[138:141], v[198:201], v[40:43]
	v_mfma_f32_16x16x32_bf16 v[28:31], v[130:133], v[206:209], v[28:31]
	v_mfma_f32_16x16x32_bf16 v[24:27], v[138:141], v[206:209], v[24:27]
	v_mfma_f32_16x16x32_bf16 v[12:15], v[130:133], v[240:243], v[12:15]
	v_mfma_f32_16x16x32_bf16 v[8:11], v[138:141], v[240:243], v[8:11]
	v_mfma_f32_16x16x32_bf16 v[60:63], v[134:137], v[194:197], v[60:63]
	v_mfma_f32_16x16x32_bf16 v[56:59], v[142:145], v[194:197], v[56:59]
	v_mfma_f32_16x16x32_bf16 v[44:47], v[134:137], v[202:205], v[44:47]
	v_mfma_f32_16x16x32_bf16 v[40:43], v[142:145], v[202:205], v[40:43]
	v_mfma_f32_16x16x32_bf16 v[28:31], v[134:137], v[210:213], v[28:31]
	v_mfma_f32_16x16x32_bf16 v[24:27], v[142:145], v[210:213], v[24:27]
	v_mfma_f32_16x16x32_bf16 v[12:15], v[134:137], v[244:247], v[12:15]
	v_mfma_f32_16x16x32_bf16 v[8:11], v[142:145], v[244:247], v[8:11]
	s_setprio 0
	s_setprio 1
	v_mfma_f32_16x16x32_bf16 v[52:55], v[146:149], v[190:193], v[52:55]
	v_mfma_f32_16x16x32_bf16 v[48:51], v[154:157], v[190:193], v[48:51]
	v_mfma_f32_16x16x32_bf16 v[36:39], v[146:149], v[198:201], v[36:39]
	v_mfma_f32_16x16x32_bf16 v[32:35], v[154:157], v[198:201], v[32:35]
	v_mfma_f32_16x16x32_bf16 v[20:23], v[146:149], v[206:209], v[20:23]
	v_mfma_f32_16x16x32_bf16 v[16:19], v[154:157], v[206:209], v[16:19]
	v_mfma_f32_16x16x32_bf16 v[4:7], v[146:149], v[240:243], v[4:7]
	v_mfma_f32_16x16x32_bf16 v[0:3], v[154:157], v[240:243], v[0:3]
	v_mfma_f32_16x16x32_bf16 v[52:55], v[150:153], v[194:197], v[52:55]
	v_mfma_f32_16x16x32_bf16 v[48:51], v[186:189], v[194:197], v[48:51]
	v_mfma_f32_16x16x32_bf16 v[36:39], v[150:153], v[202:205], v[36:39]
	v_mfma_f32_16x16x32_bf16 v[32:35], v[186:189], v[202:205], v[32:35]
	v_mfma_f32_16x16x32_bf16 v[20:23], v[150:153], v[210:213], v[20:23]
	v_mfma_f32_16x16x32_bf16 v[16:19], v[186:189], v[210:213], v[16:19]
	v_mfma_f32_16x16x32_bf16 v[4:7], v[150:153], v[244:247], v[4:7]
	v_mfma_f32_16x16x32_bf16 v[0:3], v[186:189], v[244:247], v[0:3]
	s_setprio 0
	s_barrier
	s_add_u32 s12, s12, 0x100
	s_addc_u32 s13, s13, 0
	v_lshl_add_u64 v[128:129], v[128:129], 0, s[80:81]
	s_cmp_ge_u32 s47, s48
	s_mov_b32 s46, s47
	s_cbranch_scc1 .Lpl1_after

; #define PG8_BAR __builtin_amdgcn_s_barrier()
; template <class Epi, bool ALIGN_EPI>
; __device__ __forceinline__ void gemm_phase(LAS unsigned char* lds, const Gemm g, const StaticOrder& S, const Epi& E, const int tid) {
;     ...
;         if constexpr (ALIGN_EPI) { if (wr == 0) PG8_BAR; }
;         { int t2 = tid; asm volatile("" : "+v"(t2)); const int l2 = t2 & 63, w2 = __builtin_amdgcn_readfirstlane(t2 >> 6); E(acc, cur, w2 >> 2, w2 & 3, l2 & 15, l2 >> 4); }
.Lpl1_after:
	v_readlane_b32 s70, v255, 47
	s_mov_b32 s72, 0x40000
	v_readlane_b32 s71, v255, 48

; #define PG8_STAGE(bufoff, gbase, voff) do { _Pragma("unroll") for (int _i = 0; _i < 2; ++_i) \
;         __builtin_amdgcn_global_load_lds((const unsigned*)((const char*)(gbase) + (voff)[_i]), (LAS unsigned*)(lds + (bufoff) + ldsw + _i * 8192), 16, 0, 0); } while (0)
; #define PG8_LDA(dst, b, h) do { _Pragma("unroll") for (int m = 0; m < 4; ++m) _Pragma("unroll") for (int k = 0; k < 2; ++k) dst[m][k] = *(const LAS bf16x8*)(lds + PG8_SA(b, h) + aoff + m * 2048 + k * 1024); } while (0)
; #define PG8_LDB(dst, b, h) do { _Pragma("unroll") for (int n = 0; n < 2; ++n) _Pragma("unroll") for (int k = 0; k < 2; ++k) dst[n][k] = *(const LAS bf16x8*)(lds + PG8_SB(b, h) + boff + n * 2048 + k * 1024); } while (0)
; #define PG8_MMA(ai, bj, At, Bt) do { __builtin_amdgcn_s_setprio(1); _Pragma("unroll") for (int k = 0; k < 2; ++k) _Pragma("unroll") for (int m = 0; m < 4; ++m) _Pragma("unroll") for (int n = 0; n < 2; ++n) \
;         acc[ai][bj][m][n] = __builtin_amdgcn_mfma_f32_16x16x32_bf16(Bt[n][k], At[m][k], acc[ai][bj][m][n], 0, 0, 0); __builtin_amdgcn_s_setprio(0); } while (0)
; template <class Epi, bool ALIGN_EPI>
; __device__ __forceinline__ void gemm_phase(LAS unsigned char* lds, const Gemm g, const StaticOrder& S, const Epi& E, const int tid) {
;     ...
;         const bool has_next = S.next(ui + 1, nxt);
;         const char* nA = has_next ? (const char*)g.A + (size_t)nxt.pm * tA + (size_t)nxt.pn * g.apn * 2 : cA; const char* nB = has_next ? (const char*)g.Bt + (size_t)nxt.pn * tB : cB;
;         for (int t = 0; t < nt; t += 2) {
;             const bool last = (t == nt - 2);
;             const char* a1 = cA + (size_t)(t + 1) * kstep;
;             const char* a2 = last ? nA : cA + (size_t)(t + 2) * kstep; const char* b2 = last ? nB : cB + (size_t)(t + 2) * kstep;
;             const char* a3 = a2 + kstep; const char* b3 = b2 + kstep;
;             PG8_LDB(B0, 0, 0); PG8_LDB(B1, 0, 1); PG8_SCHED; PG8_LDA(At, 0, 0); PG8_STAGE(PG8_SA(1, 1), a1 + hA, voffA);
;             PG8_WAIT_V(8); PG8_WAIT_L(0); PG8_BAR; PG8_MMA(0, 0, At, B0); PG8_MMA(0, 1, At, B1); PG8_BAR; PG8_SCHED;
;             PG8_LDA(At, 0, 1); PG8_STAGE(PG8_SB(0, 0), b2, voffB); PG8_STAGE(PG8_SB(0, 1), b2 + hB, voffB); PG8_STAGE(PG8_SA(0, 0), a2, voffA);
;             PG8_WAIT_V(8); PG8_WAIT_L(0); PG8_BAR; PG8_MMA(1, 0, At, B0); PG8_MMA(1, 1, At, B1); PG8_BAR; PG8_SCHED;
.LBB0_272:
	s_andn2_b64 vcc, exec, s[36:37]
	s_cbranch_vccnz .LBB0_276
	s_add_u32 s10, s14, 0x100
	v_lshl_add_u64 v[128:129], v[128:129], 0, s[92:93]
	s_addc_u32 s11, s15, 0
	s_mov_b32 s14, 0
	s_add_i32 s15, s14, 2
	s_cmp_eq_u32 s57, s14
	s_cselect_b64 vcc, -1, 0
	s_cselect_b32 s69, s13, s11
	s_cselect_b32 s68, s12, s10
	s_add_i32 s14, 0, 0x14000
	v_lshl_add_u64 v[130:131], v[128:129], 0, s[92:93]
	v_add_u32_e32 v142, s33, v239
	v_add_u32_e32 v158, s14, v239
	v_cndmask_b32_e32 v167, v131, v191, vcc
	v_cndmask_b32_e32 v166, v130, v190, vcc
	ds_read_b128 v[130:133], v142
	ds_read_b128 v[134:137], v142 offset:1024
	ds_read_b128 v[138:141], v142 offset:2048
	ds_read_b128 v[142:145], v142 offset:3072
	ds_read_b128 v[146:149], v158
	ds_read_b128 v[150:153], v158 offset:1024
	ds_read_b128 v[154:157], v158 offset:2048
	ds_read_b128 v[158:161], v158 offset:3072
	v_lshl_add_u64 v[220:221], v[128:129], 0, v[186:187]
	s_add_i32 m0, s51, 0xc000
	ds_read_b128 v[162:165], v171
	ds_read_b128 v[192:195], v171 offset:1024
	ds_read_b128 v[196:199], v171 offset:2048
	ds_read_b128 v[200:203], v171 offset:3072
	ds_read_b128 v[204:207], v171 offset:4096
	ds_read_b128 v[208:211], v171 offset:5120
	ds_read_b128 v[212:215], v171 offset:6144
	ds_read_b128 v[216:219], v171 offset:7168
	global_load_lds_dwordx4 v[220:221], off
	v_lshl_add_u64 v[220:221], v[128:129], 0, v[188:189]
	s_add_i32 m0, s51, 0xe000
	s_nop 0
	global_load_lds_dwordx4 v[220:221], off
	s_waitcnt vmcnt(8)
	s_waitcnt lgkmcnt(0)
	s_barrier
	s_setprio 1
	s_waitcnt lgkmcnt(0)
	v_mfma_f32_16x16x32_bf16 v[124:127], v[130:133], v[162:165], 0
	v_mfma_f32_16x16x32_bf16 v[120:123], v[138:141], v[162:165], 0
	v_mfma_f32_16x16x32_bf16 v[108:111], v[130:133], v[196:199], 0
	v_mfma_f32_16x16x32_bf16 v[104:107], v[138:141], v[196:199], 0
	v_mfma_f32_16x16x32_bf16 v[92:95], v[130:133], v[204:207], 0
	v_mfma_f32_16x16x32_bf16 v[88:91], v[138:141], v[204:207], 0
	v_mfma_f32_16x16x32_bf16 v[76:79], v[130:133], v[212:215], 0
	v_mfma_f32_16x16x32_bf16 v[72:75], v[138:141], v[212:215], 0
	v_mfma_f32_16x16x32_bf16 v[124:127], v[134:137], v[192:195], v[124:127]
	v_mfma_f32_16x16x32_bf16 v[120:123], v[142:145], v[192:195], v[120:123]
	v_mfma_f32_16x16x32_bf16 v[108:111], v[134:137], v[200:203], v[108:111]
	v_mfma_f32_16x16x32_bf16 v[104:107], v[142:145], v[200:203], v[104:107]
	v_mfma_f32_16x16x32_bf16 v[92:95], v[134:137], v[208:211], v[92:95]
	v_mfma_f32_16x16x32_bf16 v[88:91], v[142:145], v[208:211], v[88:91]
	v_mfma_f32_16x16x32_bf16 v[76:79], v[134:137], v[216:219], v[76:79]
	v_mfma_f32_16x16x32_bf16 v[72:75], v[142:145], v[216:219], v[72:75]
	s_setprio 0
	s_setprio 1
	v_mfma_f32_16x16x32_bf16 v[116:119], v[146:149], v[162:165], 0
	v_mfma_f32_16x16x32_bf16 v[112:115], v[154:157], v[162:165], 0
	v_mfma_f32_16x16x32_bf16 v[100:103], v[146:149], v[196:199], 0
	v_mfma_f32_16x16x32_bf16 v[96:99], v[154:157], v[196:199], 0
	v_mfma_f32_16x16x32_bf16 v[84:87], v[146:149], v[204:207], 0
	v_mfma_f32_16x16x32_bf16 v[80:83], v[154:157], v[204:207], 0
	v_mfma_f32_16x16x32_bf16 v[68:71], v[146:149], v[212:215], 0
	v_mfma_f32_16x16x32_bf16 v[64:67], v[154:157], v[212:215], 0
	v_mfma_f32_16x16x32_bf16 v[116:119], v[150:153], v[192:195], v[116:119]
	v_mfma_f32_16x16x32_bf16 v[112:115], v[158:161], v[192:195], v[112:115]
	v_mfma_f32_16x16x32_bf16 v[100:103], v[150:153], v[200:203], v[100:103]
	v_mfma_f32_16x16x32_bf16 v[96:99], v[158:161], v[200:203], v[96:99]
	v_mfma_f32_16x16x32_bf16 v[84:87], v[150:153], v[208:211], v[84:87]
	v_mfma_f32_16x16x32_bf16 v[80:83], v[158:161], v[208:211], v[80:83]
	v_mfma_f32_16x16x32_bf16 v[68:71], v[150:153], v[216:219], v[68:71]
	v_mfma_f32_16x16x32_bf16 v[64:67], v[158:161], v[216:219], v[64:67]
	s_setprio 0
	s_barrier
	s_add_i32 s70, s33, s47
	v_lshl_add_u64 v[220:221], s[68:69], 0, v[180:181]
	s_mov_b32 m0, s70
	ds_read_b128 v[162:165], v171 offset:16384
	ds_read_b128 v[192:195], v171 offset:17408
	ds_read_b128 v[196:199], v171 offset:18432
	ds_read_b128 v[200:203], v171 offset:19456
	ds_read_b128 v[204:207], v171 offset:20480
	ds_read_b128 v[208:211], v171 offset:21504
	ds_read_b128 v[212:215], v171 offset:22528
	ds_read_b128 v[216:219], v171 offset:23552
	global_load_lds_dwordx4 v[220:221], off
	s_add_i32 m0, s70, 0x2000
	v_lshl_add_u64 v[226:227], s[68:69], 0, v[184:185]
	s_add_u32 s68, s68, s49
	s_addc_u32 s69, s69, 0
	s_add_i32 s14, s14, s47
	global_load_lds_dwordx4 v[226:227], off
	v_lshl_add_u64 v[240:241], s[68:69], 0, v[180:181]
	s_mov_b32 m0, s14
	v_lshl_add_u64 v[242:243], s[68:69], 0, v[184:185]
	global_load_lds_dwordx4 v[240:241], off
	s_add_i32 m0, s14, 0x2000
	v_lshl_add_u64 v[244:245], v[166:167], 0, v[178:179]
	global_load_lds_dwordx4 v[242:243], off
	s_mov_b32 m0, s51
	v_lshl_add_u64 v[246:247], v[166:167], 0, v[182:183]
	global_load_lds_dwordx4 v[244:245], off
	s_mov_b32 m0, s52
	s_nop 0
	global_load_lds_dwordx4 v[246:247], off
	s_waitcnt vmcnt(8)
	s_waitcnt lgkmcnt(0)
	s_barrier
; #define PG8_STAGE(bufoff, gbase, voff) do { _Pragma("unroll") for (int _i = 0; _i < 2; ++_i) \
;         __builtin_amdgcn_global_load_lds((const unsigned*)((const char*)(gbase) + (voff)[_i]), (LAS unsigned*)(lds + (bufoff) + ldsw + _i * 8192), 16, 0, 0); } while (0)
; #define PG8_LDA(dst, b, h) do { _Pragma("unroll") for (int m = 0; m < 4; ++m) _Pragma("unroll") for (int k = 0; k < 2; ++k) dst[m][k] = *(const LAS bf16x8*)(lds + PG8_SA(b, h) + aoff + m * 2048 + k * 1024); } while (0)
; #define PG8_LDB(dst, b, h) do { _Pragma("unroll") for (int n = 0; n < 2; ++n) _Pragma("unroll") for (int k = 0; k < 2; ++k) dst[n][k] = *(const LAS bf16x8*)(lds + PG8_SB(b, h) + boff + n * 2048 + k * 1024); } while (0)
; #define PG8_MMA(ai, bj, At, Bt) do { __builtin_amdgcn_s_setprio(1); _Pragma("unroll") for (int k = 0; k < 2; ++k) _Pragma("unroll") for (int m = 0; m < 4; ++m) _Pragma("unroll") for (int n = 0; n < 2; ++n) \
;         acc[ai][bj][m][n] = __builtin_amdgcn_mfma_f32_16x16x32_bf16(Bt[n][k], At[m][k], acc[ai][bj][m][n], 0, 0, 0); __builtin_amdgcn_s_setprio(0); } while (0)
; #define PG8_WAIT_V(n) asm volatile("s_waitcnt vmcnt(" #n ")" ::: "memory")
; #define PG8_WAIT_L(n) asm volatile("s_waitcnt lgkmcnt(" #n ")" ::: "memory")
; #define PG8_BAR __builtin_amdgcn_s_barrier()
; #define PG8_SCHED __builtin_amdgcn_sched_barrier(0)
; template <class Epi, bool ALIGN_EPI>
; __device__ __forceinline__ void gemm_phase(LAS unsigned char* lds, const Gemm g, const StaticOrder& S, const Epi& E, const int tid) {
;     ...
;             PG8_WAIT_V(8); PG8_WAIT_L(0); PG8_BAR; PG8_MMA(1, 0, At, B0); PG8_MMA(1, 1, At, B1); PG8_BAR; PG8_SCHED;
;             PG8_LDB(B0, 1, 0); PG8_LDB(B1, 1, 1); PG8_SCHED; PG8_LDA(At, 1, 0); PG8_STAGE(PG8_SA(0, 1), a2 + hA, voffA);
;             PG8_WAIT_V(8); PG8_WAIT_L(0); PG8_BAR; PG8_MMA(0, 0, At, B0); PG8_MMA(0, 1, At, B1); PG8_BAR; PG8_SCHED;
;             PG8_LDA(At, 1, 1); PG8_STAGE(PG8_SB(1, 0), b3, voffB); PG8_STAGE(PG8_SB(1, 1), b3 + hB, voffB); PG8_STAGE(PG8_SA(1, 0), a3, voffA);
	s_setprio 1
	s_waitcnt lgkmcnt(0)
	v_mfma_f32_16x16x32_bf16 v[60:63], v[130:133], v[162:165], 0
	v_mfma_f32_16x16x32_bf16 v[56:59], v[138:141], v[162:165], 0
	v_mfma_f32_16x16x32_bf16 v[44:47], v[130:133], v[196:199], 0
	v_mfma_f32_16x16x32_bf16 v[40:43], v[138:141], v[196:199], 0
	v_mfma_f32_16x16x32_bf16 v[28:31], v[130:133], v[204:207], 0
	v_mfma_f32_16x16x32_bf16 v[24:27], v[138:141], v[204:207], 0
	v_mfma_f32_16x16x32_bf16 v[12:15], v[130:133], v[212:215], 0
	v_mfma_f32_16x16x32_bf16 v[8:11], v[138:141], v[212:215], 0
	v_mfma_f32_16x16x32_bf16 v[60:63], v[134:137], v[192:195], v[60:63]
	v_mfma_f32_16x16x32_bf16 v[56:59], v[142:145], v[192:195], v[56:59]
	v_mfma_f32_16x16x32_bf16 v[44:47], v[134:137], v[200:203], v[44:47]
	v_mfma_f32_16x16x32_bf16 v[40:43], v[142:145], v[200:203], v[40:43]
	v_mfma_f32_16x16x32_bf16 v[28:31], v[134:137], v[208:211], v[28:31]
	v_mfma_f32_16x16x32_bf16 v[24:27], v[142:145], v[208:211], v[24:27]
	v_mfma_f32_16x16x32_bf16 v[12:15], v[134:137], v[216:219], v[12:15]
	v_mfma_f32_16x16x32_bf16 v[8:11], v[142:145], v[216:219], v[8:11]
	s_setprio 0
	s_setprio 1
	v_mfma_f32_16x16x32_bf16 v[52:55], v[146:149], v[162:165], 0
	v_mfma_f32_16x16x32_bf16 v[48:51], v[154:157], v[162:165], 0
	v_mfma_f32_16x16x32_bf16 v[36:39], v[146:149], v[196:199], 0
	v_mfma_f32_16x16x32_bf16 v[32:35], v[154:157], v[196:199], 0
	v_mfma_f32_16x16x32_bf16 v[20:23], v[146:149], v[204:207], 0
	v_mfma_f32_16x16x32_bf16 v[16:19], v[154:157], v[204:207], 0
	v_mfma_f32_16x16x32_bf16 v[4:7], v[146:149], v[212:215], 0
	v_mfma_f32_16x16x32_bf16 v[0:3], v[154:157], v[212:215], 0
	v_mfma_f32_16x16x32_bf16 v[52:55], v[150:153], v[192:195], v[52:55]
	v_mfma_f32_16x16x32_bf16 v[48:51], v[158:161], v[192:195], v[48:51]
	v_mfma_f32_16x16x32_bf16 v[36:39], v[150:153], v[200:203], v[36:39]
	v_mfma_f32_16x16x32_bf16 v[32:35], v[158:161], v[200:203], v[32:35]
	v_mfma_f32_16x16x32_bf16 v[20:23], v[150:153], v[208:211], v[20:23]
	v_mfma_f32_16x16x32_bf16 v[16:19], v[158:161], v[208:211], v[16:19]
	v_mfma_f32_16x16x32_bf16 v[4:7], v[150:153], v[216:219], v[4:7]
	v_mfma_f32_16x16x32_bf16 v[0:3], v[158:161], v[216:219], v[0:3]
	s_setprio 0
	s_barrier
	s_add_i32 s14, 0, 0x18000
	s_add_i32 s68, 0, 0x1c000
	v_add_u32_e32 v142, s14, v239
	v_add_u32_e32 v158, s68, v239
	ds_read_b128 v[130:133], v142
	ds_read_b128 v[134:137], v142 offset:1024
	ds_read_b128 v[138:141], v142 offset:2048
	ds_read_b128 v[142:145], v142 offset:3072
	ds_read_b128 v[146:149], v158
	ds_read_b128 v[150:153], v158 offset:1024
	ds_read_b128 v[154:157], v158 offset:2048
	ds_read_b128 v[158:161], v158 offset:3072
	v_lshl_add_u64 v[166:167], v[166:167], 0, s[94:95]
	s_mov_b32 m0, s53
	v_lshl_add_u64 v[248:249], v[166:167], 0, v[178:179]
	ds_read_b128 v[162:165], v171 offset:32768
	ds_read_b128 v[192:195], v171 offset:33792
	ds_read_b128 v[196:199], v171 offset:34816
	ds_read_b128 v[200:203], v171 offset:35840
	ds_read_b128 v[204:207], v171 offset:36864
	ds_read_b128 v[208:211], v171 offset:37888
	ds_read_b128 v[212:215], v171 offset:38912
	ds_read_b128 v[216:219], v171 offset:39936
	global_load_lds_dwordx4 v[248:249], off
	v_lshl_add_u64 v[166:167], v[166:167], 0, v[182:183]
	s_mov_b32 m0, s54
	s_nop 0
	global_load_lds_dwordx4 v[166:167], off
	s_waitcnt vmcnt(8)
	s_waitcnt lgkmcnt(0)
	s_barrier
	s_setprio 1
	s_waitcnt lgkmcnt(0)
	v_mfma_f32_16x16x32_bf16 v[124:127], v[130:133], v[162:165], v[124:127]
	v_mfma_f32_16x16x32_bf16 v[120:123], v[138:141], v[162:165], v[120:123]
	v_mfma_f32_16x16x32_bf16 v[108:111], v[130:133], v[196:199], v[108:111]
	v_mfma_f32_16x16x32_bf16 v[104:107], v[138:141], v[196:199], v[104:107]
	v_mfma_f32_16x16x32_bf16 v[92:95], v[130:133], v[204:207], v[92:95]
	v_mfma_f32_16x16x32_bf16 v[88:91], v[138:141], v[204:207], v[88:91]
	v_mfma_f32_16x16x32_bf16 v[76:79], v[130:133], v[212:215], v[76:79]
	v_mfma_f32_16x16x32_bf16 v[72:75], v[138:141], v[212:215], v[72:75]
	v_mfma_f32_16x16x32_bf16 v[124:127], v[134:137], v[192:195], v[124:127]
	v_mfma_f32_16x16x32_bf16 v[120:123], v[142:145], v[192:195], v[120:123]
	v_mfma_f32_16x16x32_bf16 v[108:111], v[134:137], v[200:203], v[108:111]
	v_mfma_f32_16x16x32_bf16 v[104:107], v[142:145], v[200:203], v[104:107]
	v_mfma_f32_16x16x32_bf16 v[92:95], v[134:137], v[208:211], v[92:95]
	v_mfma_f32_16x16x32_bf16 v[88:91], v[142:145], v[208:211], v[88:91]
	v_mfma_f32_16x16x32_bf16 v[76:79], v[134:137], v[216:219], v[76:79]
	v_mfma_f32_16x16x32_bf16 v[72:75], v[142:145], v[216:219], v[72:75]
	s_setprio 0
	s_setprio 1
	v_mfma_f32_16x16x32_bf16 v[116:119], v[146:149], v[162:165], v[116:119]
	v_mfma_f32_16x16x32_bf16 v[112:115], v[154:157], v[162:165], v[112:115]
	v_mfma_f32_16x16x32_bf16 v[100:103], v[146:149], v[196:199], v[100:103]
	v_mfma_f32_16x16x32_bf16 v[96:99], v[154:157], v[196:199], v[96:99]
	v_mfma_f32_16x16x32_bf16 v[84:87], v[146:149], v[204:207], v[84:87]
	v_mfma_f32_16x16x32_bf16 v[80:83], v[154:157], v[204:207], v[80:83]
	v_mfma_f32_16x16x32_bf16 v[68:71], v[146:149], v[212:215], v[68:71]
	v_mfma_f32_16x16x32_bf16 v[64:67], v[154:157], v[212:215], v[64:67]
	v_mfma_f32_16x16x32_bf16 v[116:119], v[150:153], v[192:195], v[116:119]
	v_mfma_f32_16x16x32_bf16 v[112:115], v[158:161], v[192:195], v[112:115]
	v_mfma_f32_16x16x32_bf16 v[100:103], v[150:153], v[200:203], v[100:103]
	v_mfma_f32_16x16x32_bf16 v[96:99], v[158:161], v[200:203], v[96:99]
	v_mfma_f32_16x16x32_bf16 v[84:87], v[150:153], v[208:211], v[84:87]
	v_mfma_f32_16x16x32_bf16 v[80:83], v[158:161], v[208:211], v[80:83]
	v_mfma_f32_16x16x32_bf16 v[68:71], v[150:153], v[216:219], v[68:71]
	v_mfma_f32_16x16x32_bf16 v[64:67], v[158:161], v[216:219], v[64:67]
	s_setprio 0
	s_barrier
; #define PG8_STAGE(bufoff, gbase, voff) do { _Pragma("unroll") for (int _i = 0; _i < 2; ++_i) \
;         __builtin_amdgcn_global_load_lds((const unsigned*)((const char*)(gbase) + (voff)[_i]), (LAS unsigned*)(lds + (bufoff) + ldsw + _i * 8192), 16, 0, 0); } while (0)
; #define PG8_LDA(dst, b, h) do { _Pragma("unroll") for (int m = 0; m < 4; ++m) _Pragma("unroll") for (int k = 0; k < 2; ++k) dst[m][k] = *(const LAS bf16x8*)(lds + PG8_SA(b, h) + aoff + m * 2048 + k * 1024); } while (0)
; #define PG8_MMA(ai, bj, At, Bt) do { __builtin_amdgcn_s_setprio(1); _Pragma("unroll") for (int k = 0; k < 2; ++k) _Pragma("unroll") for (int m = 0; m < 4; ++m) _Pragma("unroll") for (int n = 0; n < 2; ++n) \
;         acc[ai][bj][m][n] = __builtin_amdgcn_mfma_f32_16x16x32_bf16(Bt[n][k], At[m][k], acc[ai][bj][m][n], 0, 0, 0); __builtin_amdgcn_s_setprio(0); } while (0)
; #define PG8_WAIT_V(n) asm volatile("s_waitcnt vmcnt(" #n ")" ::: "memory")
; #define PG8_WAIT_L(n) asm volatile("s_waitcnt lgkmcnt(" #n ")" ::: "memory")
; #define PG8_BAR __builtin_amdgcn_s_barrier()
; #define PG8_SCHED __builtin_amdgcn_sched_barrier(0)
; template <class Epi, bool ALIGN_EPI>
; __device__ __forceinline__ void gemm_phase(LAS unsigned char* lds, const Gemm g, const StaticOrder& S, const Epi& E, const int tid) {
;     ...
;             PG8_LDA(At, 1, 1); PG8_STAGE(PG8_SB(1, 0), b3, voffB); PG8_STAGE(PG8_SB(1, 1), b3 + hB, voffB); PG8_STAGE(PG8_SA(1, 0), a3, voffA);
;             PG8_WAIT_V(8); PG8_WAIT_L(0); PG8_BAR; PG8_MMA(1, 0, At, B0); PG8_MMA(1, 1, At, B1); PG8_BAR; PG8_SCHED;
;         }
	s_add_i32 s14, s14, s47
	v_lshl_add_u64 v[166:167], v[220:221], 0, s[92:93]
	s_mov_b32 m0, s14
	ds_read_b128 v[162:165], v171 offset:49152
	ds_read_b128 v[192:195], v171 offset:50176
	ds_read_b128 v[196:199], v171 offset:51200
	ds_read_b128 v[200:203], v171 offset:52224
	ds_read_b128 v[204:207], v171 offset:53248
	ds_read_b128 v[208:211], v171 offset:54272
	ds_read_b128 v[212:215], v171 offset:55296
	ds_read_b128 v[216:219], v171 offset:56320
	global_load_lds_dwordx4 v[166:167], off
	v_lshl_add_u64 v[166:167], v[226:227], 0, s[92:93]
	s_add_i32 m0, s14, 0x2000
	s_add_i32 s14, s68, s47
	global_load_lds_dwordx4 v[166:167], off
	v_lshl_add_u64 v[166:167], v[240:241], 0, s[92:93]
	s_mov_b32 m0, s14
	s_nop 0
	global_load_lds_dwordx4 v[166:167], off
	v_lshl_add_u64 v[166:167], v[242:243], 0, s[92:93]
	s_add_i32 m0, s14, 0x2000
	s_nop 0
	global_load_lds_dwordx4 v[166:167], off
	v_lshl_add_u64 v[166:167], v[244:245], 0, s[92:93]
	s_mov_b32 m0, s55
	s_nop 0
	global_load_lds_dwordx4 v[166:167], off
	v_lshl_add_u64 v[166:167], v[246:247], 0, s[92:93]
	s_mov_b32 m0, s56
	s_nop 0
	global_load_lds_dwordx4 v[166:167], off
	s_waitcnt vmcnt(8)
	s_waitcnt lgkmcnt(0)
	s_barrier
	s_setprio 1
	s_waitcnt lgkmcnt(0)
	v_mfma_f32_16x16x32_bf16 v[60:63], v[130:133], v[162:165], v[60:63]
	v_mfma_f32_16x16x32_bf16 v[56:59], v[138:141], v[162:165], v[56:59]
	v_mfma_f32_16x16x32_bf16 v[44:47], v[130:133], v[196:199], v[44:47]
	v_mfma_f32_16x16x32_bf16 v[40:43], v[138:141], v[196:199], v[40:43]
	v_mfma_f32_16x16x32_bf16 v[28:31], v[130:133], v[204:207], v[28:31]
	v_mfma_f32_16x16x32_bf16 v[24:27], v[138:141], v[204:207], v[24:27]
	v_mfma_f32_16x16x32_bf16 v[12:15], v[130:133], v[212:215], v[12:15]
	v_mfma_f32_16x16x32_bf16 v[8:11], v[138:141], v[212:215], v[8:11]
	v_mfma_f32_16x16x32_bf16 v[60:63], v[134:137], v[192:195], v[60:63]
	v_mfma_f32_16x16x32_bf16 v[56:59], v[142:145], v[192:195], v[56:59]
	v_mfma_f32_16x16x32_bf16 v[44:47], v[134:137], v[200:203], v[44:47]
	v_mfma_f32_16x16x32_bf16 v[40:43], v[142:145], v[200:203], v[40:43]
	v_mfma_f32_16x16x32_bf16 v[28:31], v[134:137], v[208:211], v[28:31]
	v_mfma_f32_16x16x32_bf16 v[24:27], v[142:145], v[208:211], v[24:27]
	v_mfma_f32_16x16x32_bf16 v[12:15], v[134:137], v[216:219], v[12:15]
	v_mfma_f32_16x16x32_bf16 v[8:11], v[142:145], v[216:219], v[8:11]
	s_setprio 0
	s_setprio 1
	v_mfma_f32_16x16x32_bf16 v[52:55], v[146:149], v[162:165], v[52:55]
	v_mfma_f32_16x16x32_bf16 v[48:51], v[154:157], v[162:165], v[48:51]
	v_mfma_f32_16x16x32_bf16 v[36:39], v[146:149], v[196:199], v[36:39]
	v_mfma_f32_16x16x32_bf16 v[32:35], v[154:157], v[196:199], v[32:35]
	v_mfma_f32_16x16x32_bf16 v[20:23], v[146:149], v[204:207], v[20:23]
	v_mfma_f32_16x16x32_bf16 v[16:19], v[154:157], v[204:207], v[16:19]
	v_mfma_f32_16x16x32_bf16 v[4:7], v[146:149], v[212:215], v[4:7]
	v_mfma_f32_16x16x32_bf16 v[0:3], v[154:157], v[212:215], v[0:3]
	v_mfma_f32_16x16x32_bf16 v[52:55], v[150:153], v[192:195], v[52:55]
	v_mfma_f32_16x16x32_bf16 v[48:51], v[158:161], v[192:195], v[48:51]
	v_mfma_f32_16x16x32_bf16 v[36:39], v[150:153], v[200:203], v[36:39]
	v_mfma_f32_16x16x32_bf16 v[32:35], v[158:161], v[200:203], v[32:35]
	v_mfma_f32_16x16x32_bf16 v[20:23], v[150:153], v[208:211], v[20:23]
	v_mfma_f32_16x16x32_bf16 v[16:19], v[158:161], v[208:211], v[16:19]
	v_mfma_f32_16x16x32_bf16 v[4:7], v[150:153], v[216:219], v[4:7]
	v_mfma_f32_16x16x32_bf16 v[0:3], v[158:161], v[216:219], v[0:3]
	s_setprio 0
	s_barrier
	s_add_u32 s10, s10, 0x100
	s_addc_u32 s11, s11, 0
	v_lshl_add_u64 v[128:129], v[128:129], 0, s[80:81]
	s_cmp_ge_u32 s15, s48
	s_mov_b32 s14, s15
	s_cbranch_scc1 .Lpl2_after

; #define PG8_BAR __builtin_amdgcn_s_barrier()
; template <class Epi, bool ALIGN_EPI>
; __device__ __forceinline__ void gemm_phase(LAS unsigned char* lds, const Gemm g, const StaticOrder& S, const Epi& E, const int tid) {
;     ...
;         if constexpr (ALIGN_EPI) { if (wr == 0) PG8_BAR; }
;         { int t2 = tid; asm volatile("" : "+v"(t2)); const int l2 = t2 & 63, w2 = __builtin_amdgcn_readfirstlane(t2 >> 6); E(acc, cur, w2 >> 2, w2 & 3, l2 & 15, l2 >> 4); }
.Lpl2_after:
	s_mov_b64 s[70:71], s[90:91]

; #define PG8_STAGE(bufoff, gbase, voff) do { _Pragma("unroll") for (int _i = 0; _i < 2; ++_i) \
;         __builtin_amdgcn_global_load_lds((const unsigned*)((const char*)(gbase) + (voff)[_i]), (LAS unsigned*)(lds + (bufoff) + ldsw + _i * 8192), 16, 0, 0); } while (0)
; #define PG8_LDA(dst, b, h) do { _Pragma("unroll") for (int m = 0; m < 4; ++m) _Pragma("unroll") for (int k = 0; k < 2; ++k) dst[m][k] = *(const LAS bf16x8*)(lds + PG8_SA(b, h) + aoff + m * 2048 + k * 1024); } while (0)
; #define PG8_LDB(dst, b, h) do { _Pragma("unroll") for (int n = 0; n < 2; ++n) _Pragma("unroll") for (int k = 0; k < 2; ++k) dst[n][k] = *(const LAS bf16x8*)(lds + PG8_SB(b, h) + boff + n * 2048 + k * 1024); } while (0)
; #define PG8_MMA(ai, bj, At, Bt) do { __builtin_amdgcn_s_setprio(1); _Pragma("unroll") for (int k = 0; k < 2; ++k) _Pragma("unroll") for (int m = 0; m < 4; ++m) _Pragma("unroll") for (int n = 0; n < 2; ++n) \
;         acc[ai][bj][m][n] = __builtin_amdgcn_mfma_f32_16x16x32_bf16(Bt[n][k], At[m][k], acc[ai][bj][m][n], 0, 0, 0); __builtin_amdgcn_s_setprio(0); } while (0)
; template <class Epi, bool ALIGN_EPI>
; __device__ __forceinline__ void gemm_phase(LAS unsigned char* lds, const Gemm g, const StaticOrder& S, const Epi& E, const int tid) {
;     ...
;         const bool has_next = S.next(ui + 1, nxt);
;         const char* nA = has_next ? (const char*)g.A + (size_t)nxt.pm * tA + (size_t)nxt.pn * g.apn * 2 : cA; const char* nB = has_next ? (const char*)g.Bt + (size_t)nxt.pn * tB : cB;
;         for (int t = 0; t < nt; t += 2) {
;             const bool last = (t == nt - 2);
;             const char* a1 = cA + (size_t)(t + 1) * kstep;
;             const char* a2 = last ? nA : cA + (size_t)(t + 2) * kstep; const char* b2 = last ? nB : cB + (size_t)(t + 2) * kstep;
;             const char* a3 = a2 + kstep; const char* b3 = b2 + kstep;
;             PG8_LDB(B0, 0, 0); PG8_LDB(B1, 0, 1); PG8_SCHED; PG8_LDA(At, 0, 0); PG8_STAGE(PG8_SA(1, 1), a1 + hA, voffA);
;             PG8_WAIT_V(8); PG8_WAIT_L(0); PG8_BAR; PG8_MMA(0, 0, At, B0); PG8_MMA(0, 1, At, B1); PG8_BAR; PG8_SCHED;
;             PG8_LDA(At, 0, 1); PG8_STAGE(PG8_SB(0, 0), b2, voffB); PG8_STAGE(PG8_SB(0, 1), b2 + hB, voffB); PG8_STAGE(PG8_SA(0, 0), a2, voffA);
;             PG8_WAIT_V(8); PG8_WAIT_L(0); PG8_BAR; PG8_MMA(1, 0, At, B0); PG8_MMA(1, 1, At, B1); PG8_BAR; PG8_SCHED;
.LBB0_329:
	s_andn2_b64 vcc, exec, s[36:37]
	s_cbranch_vccnz .LBB0_332
	v_lshl_add_u64 v[142:143], v[142:143], 0, s[92:93]
	v_lshl_add_u64 v[144:145], v[144:145], 0, s[80:81]
	s_mov_b32 s10, 0
	s_add_i32 s11, s10, 2
	s_cmp_eq_u32 s58, s10
	v_lshl_add_u64 v[146:147], v[142:143], 0, s[92:93]
	s_cselect_b64 vcc, -1, 0
	v_add_u32_e32 v152, s33, v153
	s_add_i32 s10, 0, 0x14000
	v_cndmask_b32_e32 v151, v147, v139, vcc
	v_cndmask_b32_e32 v150, v146, v138, vcc
	ds_read_b128 v[146:149], v152
	ds_read_b128 v[156:159], v152 offset:1024
	ds_read_b128 v[160:163], v152 offset:2048
	ds_read_b128 v[164:167], v152 offset:3072
	v_add_u32_e32 v152, s10, v153
	ds_read_b128 v[176:179], v152
	ds_read_b128 v[180:183], v152 offset:1024
	ds_read_b128 v[184:187], v152 offset:2048
	ds_read_b128 v[188:191], v152 offset:3072
	v_cndmask_b32_e32 v221, v145, v141, vcc
	v_cndmask_b32_e32 v220, v144, v140, vcc
	v_lshl_add_u64 v[226:227], v[142:143], 0, v[134:135]
	s_add_i32 m0, s51, 0xc000
	ds_read_b128 v[192:195], v155
	ds_read_b128 v[196:199], v155 offset:1024
	ds_read_b128 v[200:203], v155 offset:2048
	ds_read_b128 v[204:207], v155 offset:3072
	ds_read_b128 v[208:211], v155 offset:4096
	ds_read_b128 v[212:215], v155 offset:5120
	ds_read_b128 v[216:219], v155 offset:6144
	ds_read_b128 v[240:243], v155 offset:7168
	global_load_lds_dwordx4 v[226:227], off
	v_lshl_add_u64 v[226:227], v[142:143], 0, v[136:137]
	s_add_i32 m0, s51, 0xe000
	s_nop 0
	global_load_lds_dwordx4 v[226:227], off
	s_waitcnt vmcnt(8)
	s_waitcnt lgkmcnt(0)
	s_barrier
	s_setprio 1
	s_waitcnt lgkmcnt(0)
	v_mfma_f32_16x16x32_bf16 v[120:123], v[146:149], v[192:195], 0
	v_mfma_f32_16x16x32_bf16 v[124:127], v[160:163], v[192:195], 0
	v_mfma_f32_16x16x32_bf16 v[108:111], v[146:149], v[200:203], 0
	v_mfma_f32_16x16x32_bf16 v[104:107], v[160:163], v[200:203], 0
	v_mfma_f32_16x16x32_bf16 v[92:95], v[146:149], v[208:211], 0
	v_mfma_f32_16x16x32_bf16 v[88:91], v[160:163], v[208:211], 0
	v_mfma_f32_16x16x32_bf16 v[76:79], v[146:149], v[216:219], 0
	v_mfma_f32_16x16x32_bf16 v[72:75], v[160:163], v[216:219], 0
	v_mfma_f32_16x16x32_bf16 v[120:123], v[156:159], v[196:199], v[120:123]
	v_mfma_f32_16x16x32_bf16 v[124:127], v[164:167], v[196:199], v[124:127]
	v_mfma_f32_16x16x32_bf16 v[108:111], v[156:159], v[204:207], v[108:111]
	v_mfma_f32_16x16x32_bf16 v[104:107], v[164:167], v[204:207], v[104:107]
	v_mfma_f32_16x16x32_bf16 v[92:95], v[156:159], v[212:215], v[92:95]
	v_mfma_f32_16x16x32_bf16 v[88:91], v[164:167], v[212:215], v[88:91]
	v_mfma_f32_16x16x32_bf16 v[76:79], v[156:159], v[240:243], v[76:79]
	v_mfma_f32_16x16x32_bf16 v[72:75], v[164:167], v[240:243], v[72:75]
	s_setprio 0
	s_setprio 1
	v_mfma_f32_16x16x32_bf16 v[116:119], v[176:179], v[192:195], 0
	v_mfma_f32_16x16x32_bf16 v[112:115], v[184:187], v[192:195], 0
	v_mfma_f32_16x16x32_bf16 v[100:103], v[176:179], v[200:203], 0
	v_mfma_f32_16x16x32_bf16 v[96:99], v[184:187], v[200:203], 0
	v_mfma_f32_16x16x32_bf16 v[84:87], v[176:179], v[208:211], 0
	v_mfma_f32_16x16x32_bf16 v[80:83], v[184:187], v[208:211], 0
	v_mfma_f32_16x16x32_bf16 v[68:71], v[176:179], v[216:219], 0
	v_mfma_f32_16x16x32_bf16 v[64:67], v[184:187], v[216:219], 0
	v_mfma_f32_16x16x32_bf16 v[116:119], v[180:183], v[196:199], v[116:119]
	v_mfma_f32_16x16x32_bf16 v[112:115], v[188:191], v[196:199], v[112:115]
	v_mfma_f32_16x16x32_bf16 v[100:103], v[180:183], v[204:207], v[100:103]
	v_mfma_f32_16x16x32_bf16 v[96:99], v[188:191], v[204:207], v[96:99]
	v_mfma_f32_16x16x32_bf16 v[84:87], v[180:183], v[212:215], v[84:87]
	v_mfma_f32_16x16x32_bf16 v[80:83], v[188:191], v[212:215], v[80:83]
	v_mfma_f32_16x16x32_bf16 v[68:71], v[180:183], v[240:243], v[68:71]
	v_mfma_f32_16x16x32_bf16 v[64:67], v[188:191], v[240:243], v[64:67]
	s_setprio 0
	s_barrier
	s_add_i32 s65, s33, s45
	v_lshl_add_u64 v[226:227], v[220:221], 0, v[168:169]
	s_mov_b32 m0, s65
	ds_read_b128 v[192:195], v155 offset:16384
	ds_read_b128 v[196:199], v155 offset:17408
	ds_read_b128 v[200:203], v155 offset:18432
	ds_read_b128 v[204:207], v155 offset:19456
	ds_read_b128 v[208:211], v155 offset:20480
	ds_read_b128 v[212:215], v155 offset:21504
	ds_read_b128 v[216:219], v155 offset:22528
	ds_read_b128 v[240:243], v155 offset:23552
	global_load_lds_dwordx4 v[226:227], off
	v_lshl_add_u64 v[244:245], v[220:221], 0, v[128:129]
	s_add_i32 m0, s65, 0x2000
	v_lshl_add_u64 v[220:221], v[220:221], 0, s[12:13]
	s_add_i32 s10, s10, s45
	global_load_lds_dwordx4 v[244:245], off
	v_lshl_add_u64 v[246:247], v[220:221], 0, v[168:169]
	s_mov_b32 m0, s10
	v_lshl_add_u64 v[220:221], v[220:221], 0, v[128:129]
	global_load_lds_dwordx4 v[246:247], off
	s_add_i32 m0, s10, 0x2000
	v_lshl_add_u64 v[248:249], v[150:151], 0, v[132:133]
	global_load_lds_dwordx4 v[220:221], off
	s_mov_b32 m0, s51
	v_lshl_add_u64 v[250:251], v[150:151], 0, v[130:131]
	global_load_lds_dwordx4 v[248:249], off
	s_mov_b32 m0, s52
	s_nop 0
	global_load_lds_dwordx4 v[250:251], off
	s_waitcnt vmcnt(8)
	s_waitcnt lgkmcnt(0)
	s_barrier
; #define PG8_STAGE(bufoff, gbase, voff) do { _Pragma("unroll") for (int _i = 0; _i < 2; ++_i) \
;         __builtin_amdgcn_global_load_lds((const unsigned*)((const char*)(gbase) + (voff)[_i]), (LAS unsigned*)(lds + (bufoff) + ldsw + _i * 8192), 16, 0, 0); } while (0)
; #define PG8_LDA(dst, b, h) do { _Pragma("unroll") for (int m = 0; m < 4; ++m) _Pragma("unroll") for (int k = 0; k < 2; ++k) dst[m][k] = *(const LAS bf16x8*)(lds + PG8_SA(b, h) + aoff + m * 2048 + k * 1024); } while (0)
; #define PG8_LDB(dst, b, h) do { _Pragma("unroll") for (int n = 0; n < 2; ++n) _Pragma("unroll") for (int k = 0; k < 2; ++k) dst[n][k] = *(const LAS bf16x8*)(lds + PG8_SB(b, h) + boff + n * 2048 + k * 1024); } while (0)
; #define PG8_MMA(ai, bj, At, Bt) do { __builtin_amdgcn_s_setprio(1); _Pragma("unroll") for (int k = 0; k < 2; ++k) _Pragma("unroll") for (int m = 0; m < 4; ++m) _Pragma("unroll") for (int n = 0; n < 2; ++n) \
;         acc[ai][bj][m][n] = __builtin_amdgcn_mfma_f32_16x16x32_bf16(Bt[n][k], At[m][k], acc[ai][bj][m][n], 0, 0, 0); __builtin_amdgcn_s_setprio(0); } while (0)
; #define PG8_WAIT_V(n) asm volatile("s_waitcnt vmcnt(" #n ")" ::: "memory")
; #define PG8_WAIT_L(n) asm volatile("s_waitcnt lgkmcnt(" #n ")" ::: "memory")
; #define PG8_BAR __builtin_amdgcn_s_barrier()
; #define PG8_SCHED __builtin_amdgcn_sched_barrier(0)
; template <class Epi, bool ALIGN_EPI>
; __device__ __forceinline__ void gemm_phase(LAS unsigned char* lds, const Gemm g, const StaticOrder& S, const Epi& E, const int tid) {
;     ...
;             PG8_WAIT_V(8); PG8_WAIT_L(0); PG8_BAR; PG8_MMA(1, 0, At, B0); PG8_MMA(1, 1, At, B1); PG8_BAR; PG8_SCHED;
;             PG8_LDB(B0, 1, 0); PG8_LDB(B1, 1, 1); PG8_SCHED; PG8_LDA(At, 1, 0); PG8_STAGE(PG8_SA(0, 1), a2 + hA, voffA);
;             PG8_WAIT_V(8); PG8_WAIT_L(0); PG8_BAR; PG8_MMA(0, 0, At, B0); PG8_MMA(0, 1, At, B1); PG8_BAR; PG8_SCHED;
;             PG8_LDA(At, 1, 1); PG8_STAGE(PG8_SB(1, 0), b3, voffB); PG8_STAGE(PG8_SB(1, 1), b3 + hB, voffB); PG8_STAGE(PG8_SA(1, 0), a3, voffA);
	s_setprio 1
	s_waitcnt lgkmcnt(0)
	v_mfma_f32_16x16x32_bf16 v[60:63], v[146:149], v[192:195], 0
	v_mfma_f32_16x16x32_bf16 v[56:59], v[160:163], v[192:195], 0
	v_mfma_f32_16x16x32_bf16 v[44:47], v[146:149], v[200:203], 0
	v_mfma_f32_16x16x32_bf16 v[40:43], v[160:163], v[200:203], 0
	v_mfma_f32_16x16x32_bf16 v[28:31], v[146:149], v[208:211], 0
	v_mfma_f32_16x16x32_bf16 v[24:27], v[160:163], v[208:211], 0
	v_mfma_f32_16x16x32_bf16 v[12:15], v[146:149], v[216:219], 0
	v_mfma_f32_16x16x32_bf16 v[8:11], v[160:163], v[216:219], 0
	v_mfma_f32_16x16x32_bf16 v[60:63], v[156:159], v[196:199], v[60:63]
	v_mfma_f32_16x16x32_bf16 v[56:59], v[164:167], v[196:199], v[56:59]
	v_mfma_f32_16x16x32_bf16 v[44:47], v[156:159], v[204:207], v[44:47]
	v_mfma_f32_16x16x32_bf16 v[40:43], v[164:167], v[204:207], v[40:43]
	v_mfma_f32_16x16x32_bf16 v[28:31], v[156:159], v[212:215], v[28:31]
	v_mfma_f32_16x16x32_bf16 v[24:27], v[164:167], v[212:215], v[24:27]
	v_mfma_f32_16x16x32_bf16 v[12:15], v[156:159], v[240:243], v[12:15]
	v_mfma_f32_16x16x32_bf16 v[8:11], v[164:167], v[240:243], v[8:11]
	s_setprio 0
	s_setprio 1
	v_mfma_f32_16x16x32_bf16 v[52:55], v[176:179], v[192:195], 0
	v_mfma_f32_16x16x32_bf16 v[48:51], v[184:187], v[192:195], 0
	v_mfma_f32_16x16x32_bf16 v[36:39], v[176:179], v[200:203], 0
	v_mfma_f32_16x16x32_bf16 v[32:35], v[184:187], v[200:203], 0
	v_mfma_f32_16x16x32_bf16 v[20:23], v[176:179], v[208:211], 0
	v_mfma_f32_16x16x32_bf16 v[16:19], v[184:187], v[208:211], 0
	v_mfma_f32_16x16x32_bf16 v[4:7], v[176:179], v[216:219], 0
	v_mfma_f32_16x16x32_bf16 v[0:3], v[184:187], v[216:219], 0
	v_mfma_f32_16x16x32_bf16 v[52:55], v[180:183], v[196:199], v[52:55]
	v_mfma_f32_16x16x32_bf16 v[48:51], v[188:191], v[196:199], v[48:51]
	v_mfma_f32_16x16x32_bf16 v[36:39], v[180:183], v[204:207], v[36:39]
	v_mfma_f32_16x16x32_bf16 v[32:35], v[188:191], v[204:207], v[32:35]
	v_mfma_f32_16x16x32_bf16 v[20:23], v[180:183], v[212:215], v[20:23]
	v_mfma_f32_16x16x32_bf16 v[16:19], v[188:191], v[212:215], v[16:19]
	v_mfma_f32_16x16x32_bf16 v[4:7], v[180:183], v[240:243], v[4:7]
	v_mfma_f32_16x16x32_bf16 v[0:3], v[188:191], v[240:243], v[0:3]
	s_setprio 0
	s_barrier
	s_add_i32 s10, 0, 0x18000
	v_add_u32_e32 v152, s10, v153
	s_add_i32 s65, 0, 0x1c000
	ds_read_b128 v[146:149], v152
	ds_read_b128 v[156:159], v152 offset:1024
	ds_read_b128 v[160:163], v152 offset:2048
	ds_read_b128 v[164:167], v152 offset:3072
	v_add_u32_e32 v152, s65, v153
	ds_read_b128 v[176:179], v152
	ds_read_b128 v[180:183], v152 offset:1024
	ds_read_b128 v[184:187], v152 offset:2048
	ds_read_b128 v[188:191], v152 offset:3072
	v_lshl_add_u64 v[150:151], v[150:151], 0, s[94:95]
	s_mov_b32 m0, s53
	v_lshl_add_u64 v[252:253], v[150:151], 0, v[132:133]
	ds_read_b128 v[192:195], v155 offset:32768
	ds_read_b128 v[196:199], v155 offset:33792
	ds_read_b128 v[200:203], v155 offset:34816
	ds_read_b128 v[204:207], v155 offset:35840
	ds_read_b128 v[208:211], v155 offset:36864
	ds_read_b128 v[212:215], v155 offset:37888
	ds_read_b128 v[216:219], v155 offset:38912
	ds_read_b128 v[240:243], v155 offset:39936
	global_load_lds_dwordx4 v[252:253], off
	v_lshl_add_u64 v[150:151], v[150:151], 0, v[130:131]
	s_mov_b32 m0, s54
	s_nop 0
	global_load_lds_dwordx4 v[150:151], off
	s_waitcnt vmcnt(8)
	s_waitcnt lgkmcnt(0)
	s_barrier
	s_setprio 1
	s_waitcnt lgkmcnt(0)
	v_mfma_f32_16x16x32_bf16 v[120:123], v[146:149], v[192:195], v[120:123]
	v_mfma_f32_16x16x32_bf16 v[124:127], v[160:163], v[192:195], v[124:127]
	v_mfma_f32_16x16x32_bf16 v[108:111], v[146:149], v[200:203], v[108:111]
	v_mfma_f32_16x16x32_bf16 v[104:107], v[160:163], v[200:203], v[104:107]
	v_mfma_f32_16x16x32_bf16 v[92:95], v[146:149], v[208:211], v[92:95]
	v_mfma_f32_16x16x32_bf16 v[88:91], v[160:163], v[208:211], v[88:91]
	v_mfma_f32_16x16x32_bf16 v[76:79], v[146:149], v[216:219], v[76:79]
	v_mfma_f32_16x16x32_bf16 v[72:75], v[160:163], v[216:219], v[72:75]
	v_mfma_f32_16x16x32_bf16 v[120:123], v[156:159], v[196:199], v[120:123]
	v_mfma_f32_16x16x32_bf16 v[124:127], v[164:167], v[196:199], v[124:127]
	v_mfma_f32_16x16x32_bf16 v[108:111], v[156:159], v[204:207], v[108:111]
	v_mfma_f32_16x16x32_bf16 v[104:107], v[164:167], v[204:207], v[104:107]
	v_mfma_f32_16x16x32_bf16 v[92:95], v[156:159], v[212:215], v[92:95]
	v_mfma_f32_16x16x32_bf16 v[88:91], v[164:167], v[212:215], v[88:91]
	v_mfma_f32_16x16x32_bf16 v[76:79], v[156:159], v[240:243], v[76:79]
	v_mfma_f32_16x16x32_bf16 v[72:75], v[164:167], v[240:243], v[72:75]
	s_setprio 0
	s_setprio 1
	v_mfma_f32_16x16x32_bf16 v[116:119], v[176:179], v[192:195], v[116:119]
	v_mfma_f32_16x16x32_bf16 v[112:115], v[184:187], v[192:195], v[112:115]
	v_mfma_f32_16x16x32_bf16 v[100:103], v[176:179], v[200:203], v[100:103]
	v_mfma_f32_16x16x32_bf16 v[96:99], v[184:187], v[200:203], v[96:99]
	v_mfma_f32_16x16x32_bf16 v[84:87], v[176:179], v[208:211], v[84:87]
	v_mfma_f32_16x16x32_bf16 v[80:83], v[184:187], v[208:211], v[80:83]
	v_mfma_f32_16x16x32_bf16 v[68:71], v[176:179], v[216:219], v[68:71]
	v_mfma_f32_16x16x32_bf16 v[64:67], v[184:187], v[216:219], v[64:67]
	v_mfma_f32_16x16x32_bf16 v[116:119], v[180:183], v[196:199], v[116:119]
	v_mfma_f32_16x16x32_bf16 v[112:115], v[188:191], v[196:199], v[112:115]
	v_mfma_f32_16x16x32_bf16 v[100:103], v[180:183], v[204:207], v[100:103]
	v_mfma_f32_16x16x32_bf16 v[96:99], v[188:191], v[204:207], v[96:99]
	v_mfma_f32_16x16x32_bf16 v[84:87], v[180:183], v[212:215], v[84:87]
	v_mfma_f32_16x16x32_bf16 v[80:83], v[188:191], v[212:215], v[80:83]
	v_mfma_f32_16x16x32_bf16 v[68:71], v[180:183], v[240:243], v[68:71]
	v_mfma_f32_16x16x32_bf16 v[64:67], v[188:191], v[240:243], v[64:67]
	s_setprio 0
	s_barrier
; #define PG8_STAGE(bufoff, gbase, voff) do { _Pragma("unroll") for (int _i = 0; _i < 2; ++_i) \
;         __builtin_amdgcn_global_load_lds((const unsigned*)((const char*)(gbase) + (voff)[_i]), (LAS unsigned*)(lds + (bufoff) + ldsw + _i * 8192), 16, 0, 0); } while (0)
; #define PG8_LDA(dst, b, h) do { _Pragma("unroll") for (int m = 0; m < 4; ++m) _Pragma("unroll") for (int k = 0; k < 2; ++k) dst[m][k] = *(const LAS bf16x8*)(lds + PG8_SA(b, h) + aoff + m * 2048 + k * 1024); } while (0)
; #define PG8_MMA(ai, bj, At, Bt) do { __builtin_amdgcn_s_setprio(1); _Pragma("unroll") for (int k = 0; k < 2; ++k) _Pragma("unroll") for (int m = 0; m < 4; ++m) _Pragma("unroll") for (int n = 0; n < 2; ++n) \
;         acc[ai][bj][m][n] = __builtin_amdgcn_mfma_f32_16x16x32_bf16(Bt[n][k], At[m][k], acc[ai][bj][m][n], 0, 0, 0); __builtin_amdgcn_s_setprio(0); } while (0)
; #define PG8_WAIT_V(n) asm volatile("s_waitcnt vmcnt(" #n ")" ::: "memory")
; #define PG8_WAIT_L(n) asm volatile("s_waitcnt lgkmcnt(" #n ")" ::: "memory")
; #define PG8_BAR __builtin_amdgcn_s_barrier()
; #define PG8_SCHED __builtin_amdgcn_sched_barrier(0)
; template <class Epi, bool ALIGN_EPI>
; __device__ __forceinline__ void gemm_phase(LAS unsigned char* lds, const Gemm g, const StaticOrder& S, const Epi& E, const int tid) {
;     ...
;             PG8_LDA(At, 1, 1); PG8_STAGE(PG8_SB(1, 0), b3, voffB); PG8_STAGE(PG8_SB(1, 1), b3 + hB, voffB); PG8_STAGE(PG8_SA(1, 0), a3, voffA);
;             PG8_WAIT_V(8); PG8_WAIT_L(0); PG8_BAR; PG8_MMA(1, 0, At, B0); PG8_MMA(1, 1, At, B1); PG8_BAR; PG8_SCHED;
;         }
	s_add_i32 s10, s10, s45
	v_lshl_add_u64 v[150:151], v[226:227], 0, s[92:93]
	s_mov_b32 m0, s10
	ds_read_b128 v[192:195], v155 offset:49152
	ds_read_b128 v[196:199], v155 offset:50176
	ds_read_b128 v[200:203], v155 offset:51200
	ds_read_b128 v[204:207], v155 offset:52224
	ds_read_b128 v[208:211], v155 offset:53248
	ds_read_b128 v[212:215], v155 offset:54272
	ds_read_b128 v[216:219], v155 offset:55296
	ds_read_b128 v[240:243], v155 offset:56320
	global_load_lds_dwordx4 v[150:151], off
	v_lshl_add_u64 v[150:151], v[244:245], 0, s[92:93]
	s_add_i32 m0, s10, 0x2000
	s_add_i32 s10, s65, s45
	global_load_lds_dwordx4 v[150:151], off
	v_lshl_add_u64 v[150:151], v[246:247], 0, s[92:93]
	s_mov_b32 m0, s10
	s_nop 0
	global_load_lds_dwordx4 v[150:151], off
	v_lshl_add_u64 v[150:151], v[220:221], 0, s[92:93]
	s_add_i32 m0, s10, 0x2000
	s_nop 0
	global_load_lds_dwordx4 v[150:151], off
	v_lshl_add_u64 v[150:151], v[248:249], 0, s[92:93]
	s_mov_b32 m0, s56
	s_nop 0
	global_load_lds_dwordx4 v[150:151], off
	v_lshl_add_u64 v[150:151], v[250:251], 0, s[92:93]
	s_mov_b32 m0, s57
	s_nop 0
	global_load_lds_dwordx4 v[150:151], off
	s_waitcnt vmcnt(8)
	s_waitcnt lgkmcnt(0)
	s_barrier
	s_setprio 1
	s_waitcnt lgkmcnt(0)
	v_mfma_f32_16x16x32_bf16 v[60:63], v[146:149], v[192:195], v[60:63]
	v_mfma_f32_16x16x32_bf16 v[56:59], v[160:163], v[192:195], v[56:59]
	v_mfma_f32_16x16x32_bf16 v[44:47], v[146:149], v[200:203], v[44:47]
	v_mfma_f32_16x16x32_bf16 v[40:43], v[160:163], v[200:203], v[40:43]
	v_mfma_f32_16x16x32_bf16 v[28:31], v[146:149], v[208:211], v[28:31]
	v_mfma_f32_16x16x32_bf16 v[24:27], v[160:163], v[208:211], v[24:27]
	v_mfma_f32_16x16x32_bf16 v[12:15], v[146:149], v[216:219], v[12:15]
	v_mfma_f32_16x16x32_bf16 v[8:11], v[160:163], v[216:219], v[8:11]
	v_mfma_f32_16x16x32_bf16 v[60:63], v[156:159], v[196:199], v[60:63]
	v_mfma_f32_16x16x32_bf16 v[56:59], v[164:167], v[196:199], v[56:59]
	v_mfma_f32_16x16x32_bf16 v[44:47], v[156:159], v[204:207], v[44:47]
	v_mfma_f32_16x16x32_bf16 v[40:43], v[164:167], v[204:207], v[40:43]
	v_mfma_f32_16x16x32_bf16 v[28:31], v[156:159], v[212:215], v[28:31]
	v_mfma_f32_16x16x32_bf16 v[24:27], v[164:167], v[212:215], v[24:27]
	v_mfma_f32_16x16x32_bf16 v[12:15], v[156:159], v[240:243], v[12:15]
	v_mfma_f32_16x16x32_bf16 v[8:11], v[164:167], v[240:243], v[8:11]
	s_setprio 0
	s_setprio 1
	v_mfma_f32_16x16x32_bf16 v[52:55], v[176:179], v[192:195], v[52:55]
	v_mfma_f32_16x16x32_bf16 v[48:51], v[184:187], v[192:195], v[48:51]
	v_mfma_f32_16x16x32_bf16 v[36:39], v[176:179], v[200:203], v[36:39]
	v_mfma_f32_16x16x32_bf16 v[32:35], v[184:187], v[200:203], v[32:35]
	v_mfma_f32_16x16x32_bf16 v[20:23], v[176:179], v[208:211], v[20:23]
	v_mfma_f32_16x16x32_bf16 v[16:19], v[184:187], v[208:211], v[16:19]
	v_mfma_f32_16x16x32_bf16 v[4:7], v[176:179], v[216:219], v[4:7]
	v_mfma_f32_16x16x32_bf16 v[0:3], v[184:187], v[216:219], v[0:3]
	v_mfma_f32_16x16x32_bf16 v[52:55], v[180:183], v[196:199], v[52:55]
	v_mfma_f32_16x16x32_bf16 v[48:51], v[188:191], v[196:199], v[48:51]
	v_mfma_f32_16x16x32_bf16 v[36:39], v[180:183], v[204:207], v[36:39]
	v_mfma_f32_16x16x32_bf16 v[32:35], v[188:191], v[204:207], v[32:35]
	v_mfma_f32_16x16x32_bf16 v[20:23], v[180:183], v[212:215], v[20:23]
	v_mfma_f32_16x16x32_bf16 v[16:19], v[188:191], v[212:215], v[16:19]
	v_mfma_f32_16x16x32_bf16 v[4:7], v[180:183], v[240:243], v[4:7]
	v_mfma_f32_16x16x32_bf16 v[0:3], v[188:191], v[240:243], v[0:3]
	s_setprio 0
	s_barrier
	v_lshl_add_u64 v[142:143], v[142:143], 0, s[80:81]
	v_lshl_add_u64 v[144:145], v[144:145], 0, s[80:81]
	s_cmp_ge_u32 s11, s55
	s_mov_b32 s10, s11
	s_cbranch_scc1 .Lpl4_after

; #define PG8_BAR __builtin_amdgcn_s_barrier()
; template <class Epi, bool ALIGN_EPI>
; __device__ __forceinline__ void gemm_phase(LAS unsigned char* lds, const Gemm g, const StaticOrder& S, const Epi& E, const int tid) {
;     ...
;         }
;         if constexpr (ALIGN_EPI) { if (wr == 0) PG8_BAR; }
.Lpl4_after:
.LBB0_332:
	s_and_b64 vcc, exec, s[42:43]
	s_cbranch_vccz .LBB0_334
	s_barrier
